# K-rotation of the MLP-up GEMM with only two K offsets (k0=((rank&7)+(rank>>3))&1 tile pairs)
# speedup vs baseline: 1.0067x; 1.0067x over previous
; template <class Epi, class Sched, bool ALIGN_EPI = false, bool SP2 = false>
; __device__ __forceinline__ void gemm_phase(PG8_LAS unsigned char* lds, const Gemm g, const Sched& S, const Epi& E, const int tid) {
;     const int wid = __builtin_amdgcn_readfirstlane(tid >> 6), lane = tid & 63, wr = wid >> 2, wc = wid & 3, fr = lane & 15, fq = lane >> 4;
;     const int K = g.K, nt = K / BK;
;     unsigned voffA[2], voffB[2];
; #pragma unroll
;     for (int i = 0; i < 2; ++i) { int R, C; stage_rc(tid * 16 + i * 8192, R, C); const int Rb = Epi::PERM ? (2 * (R & ~31) + perm32(R & 31)) : R;
;         voffA[i] = (unsigned)(R * K + C) * 2u; voffB[i] = (unsigned)(Rb * K + C) * 2u; }
;     const size_t kstep = (size_t)(BK * 2);
;     const size_t hstep = (size_t)HALF * K * 2;
;     const size_t tstep = 2 * hstep;
;     const size_t hstepB = Epi::PERM ? (size_t)32 * K * 2 : hstep;
;     const unsigned ldsw = (unsigned)wid * 1024u;
;     const int aoff = lds_byte(wr * 64 + fr, fq * 8), boff = lds_byte(wc * 32 + fr, fq * 8);
;     ...
;     Unit cur, nxt; int ui = 0;
;     if (!S.next(0, cur)) return;
;     f32x4 acc[2][2][4][2];
;     u32x4 iw_[Epi::HAS_INIT ? 16 : 1];
;     if constexpr (Epi::HAS_INIT) E.init_issue(iw_, cur, wr, wc, fr, fq);
;     else {
; #pragma unroll
;     for (int a = 0; a < 2; ++a)
; #pragma unroll
;         for (int b = 0; b < 2; ++b)
; #pragma unroll
;             for (int m = 0; m < 4; ++m)
; #pragma unroll
;                 for (int n = 0; n < 2; ++n) acc[a][b][m][n] = (f32x4){0.f, 0.f, 0.f, 0.f};
;     }
;     bf16x8 At[4][2], B0[2][2], B1[2][2];
;     const char* cA = (const char*)g.A + (size_t)cur.pm * tstep; const char* cB = (const char*)g.Bt + (size_t)cur.pn * tstep;
;     S.a_ready(cur);
;     if constexpr (SP2) {
;         PG8_STAGE(PG8_SB(0, 0), cB, voffB); PG8_STAGE(PG8_SB(0, 1), cB + hstepB, voffB); PG8_STAGE(PG8_SA(0, 0), cA, voffA); PG8_STAGE(PG8_SA(0, 1), cA + hstep, voffA);
;         if (wr == 1) PG8_BAR;
;         PG8_WAIT_V(2); PG8_BAR;
;         PG8_STAGE(PG8_SB(1, 0), cB + kstep, voffB); PG8_STAGE(PG8_SA(1, 0), cA + kstep, voffA); PG8_STAGE(PG8_SB(1, 1), cB + hstepB + kstep, voffB);
;         PG8_WAIT_V(6); PG8_BAR;
;     } else {
;         PG8_STAGE(PG8_SB(0, 0), cB, voffB); PG8_STAGE(PG8_SA(0, 0), cA, voffA); PG8_STAGE(PG8_SB(0, 1), cB + hstepB, voffB); PG8_STAGE(PG8_SA(0, 1), cA + hstep, voffA);
;         if (wr == 1) PG8_BAR;
.LBB0_1371:
	s_or_b64 exec, exec, s[0:1]
	v_ashrrev_i32_e32 v3, 31, v152
	v_lshrrev_b32_e32 v3, 26, v3
	v_add_u32_e32 v3, v152, v3
	v_ashrrev_i32_e32 v12, 6, v3
	v_bfe_i32 v3, v152, 27, 1
	v_lshlrev_b32_e32 v4, 4, v152
	v_lshrrev_b32_e32 v3, 22, v3
	v_add_u32_e32 v3, v4, v3
	v_and_b32_e32 v3, 0xfffffc00, v3
	v_sub_u32_e32 v3, v4, v3
	v_lshrrev_b32_e32 v5, 4, v3
	s_lshl_b64 s[0:1], s[6:7], 23
	v_bitop3_b32 v3, v5, v3, 32 bitop3:0x6c
	s_add_u32 s6, s4, s0
	v_ashrrev_i32_e32 v6, 31, v3
	s_addc_u32 s7, s5, s1
	v_lshrrev_b32_e32 v6, 26, v6
	s_add_u32 s10, s6, 0x2100000
	v_add_u32_e32 v6, v3, v6
	s_addc_u32 s11, s7, 0
	v_lshlrev_b32_e32 v5, 3, v12
	v_ashrrev_i32_e32 v13, 6, v6
	v_and_b32_e32 v6, 0xc0, v6
	s_add_u32 s6, s4, 0xc300000
	v_and_b32_e32 v5, -16, v5
	v_sub_u32_e32 v3, v3, v6
	s_addc_u32 s7, s5, 0
	v_add_u32_e32 v133, v13, v5
	v_ashrrev_i16_sdwa v3, v205, sext(v3) dst_sel:DWORD dst_unused:UNUSED_PAD src0_sel:DWORD src1_sel:BYTE_0
	s_add_u32 s4, s4, 0x17100000
	v_lshlrev_b32_e32 v5, 5, v12
	v_bfe_i32 v14, v3, 0, 16
	v_lshrrev_b32_e32 v3, 2, v133
	s_addc_u32 s5, s5, 0
	v_and_b32_e32 v5, 32, v5
	v_and_b32_e32 v154, 4, v3
	v_lshrrev_b32_e32 v3, 1, v152
	v_readfirstlane_b32 s14, v152
	v_add_u32_e32 v132, v5, v14
	v_lshlrev_b32_e32 v156, 1, v133
	v_and_b32_e32 v155, 3, v13
	v_and_b32_e32 v153, 15, v152
	s_cmpk_gt_i32 s40, 0x7f
	v_and_b32_e32 v3, 24, v3
	s_waitcnt lgkmcnt(0)
	s_barrier
	s_cbranch_scc1 .LBB0_1387
	v_add_u32_e32 v4, 0x2000, v4
	v_ashrrev_i32_e32 v5, 31, v4
	v_lshrrev_b32_e32 v5, 22, v5
	v_add_u32_e32 v5, v4, v5
	v_ashrrev_i32_e32 v15, 10, v5
	v_mul_i32_i24_e32 v5, 0x400, v15
	v_sub_u32_e32 v4, v4, v5
	v_lshrrev_b32_e32 v5, 4, v4
	v_bitop3_b32 v4, v5, v4, 32 bitop3:0x6c
	v_ashrrev_i32_e32 v5, 31, v4
	v_lshrrev_b32_e32 v5, 26, v5
	v_add_u32_e32 v5, v4, v5
	v_lshlrev_b32_e32 v6, 3, v15
	v_ashrrev_i32_e32 v16, 6, v5
	v_and_b32_e32 v6, -16, v6
	s_lshr_b32 s12, s40, 29
	v_add_u32_e32 v6, v16, v6
	s_add_i32 s12, s40, s12
	v_lshrrev_b32_e32 v7, 2, v6
	v_lshlrev_b32_e32 v9, 1, v6
	v_and_b32_e32 v5, 0xc0, v5
	s_and_b32 s13, s12, -8
	v_and_b32_e32 v7, 4, v7
	v_and_b32_e32 v8, 3, v16
	v_and_b32_e32 v9, 0x1fffd8, v9
	v_sub_u32_e32 v4, v4, v5
	s_lshl_b32 s43, s27, 3
	s_sub_i32 s13, s40, s13
	v_or3_b32 v7, v8, v7, v9
	v_lshlrev_b32_e32 v8, 5, v15
	v_ashrrev_i16_sdwa v4, v205, sext(v4) dst_sel:DWORD dst_unused:UNUSED_PAD src0_sel:DWORD src1_sel:BYTE_0
	s_add_i32 s28, s43, s13
	s_ashr_i32 s12, s12, 3
	s_ashr_i32 s15, s14, 6
	v_and_b32_e32 v8, 32, v8
	v_bfe_i32 v17, v4, 0, 16
	s_sub_i32 s34, 15, s12
	s_ashr_i32 s29, s28, 31
	s_ashr_i32 s16, s14, 8
	s_lshl_b32 s42, s15, 10
	v_add_lshl_u32 v4, v8, v17, 1
	s_lshl_b64 s[12:13], s[28:29], 19
	s_lshl_b64 s[18:19], s[34:35], 19
	v_lshl_add_u32 v134, v7, 11, v4
	v_lshl_add_u32 v136, v6, 11, v4
	v_and_b32_e32 v4, 0x1fffd8, v156
	s_lshr_b32 s85, s40, 3
	s_add_i32 s85, s85, s40
	s_and_b32 s85, s85, 1
	s_lshl_b32 s85, s85, 8
	s_add_i32 s84, s85, 0x100
	s_add_u32 s36, s10, s18
	v_or3_b32 v4, v155, v4, v154
	v_lshlrev_b32_e32 v5, 1, v132
	s_addc_u32 s37, s11, s19
	s_add_u32 s36, s36, s85
	s_addc_u32 s37, s37, 0
	s_add_i32 s29, s42, 0
	v_lshl_add_u32 v138, v4, 11, v5
	s_add_i32 m0, s29, 0x10000
	v_lshl_add_u32 v140, v133, 11, v5
	global_load_lds_dwordx4 v138, s[36:37]
	s_add_i32 m0, s29, 0x12000
	s_add_u32 s18, s36, 0x10000
	global_load_lds_dwordx4 v134, s[36:37]
	s_addc_u32 s19, s37, 0
	s_add_i32 m0, s29, 0x14000
	v_mov_b32_e32 v139, v2
	global_load_lds_dwordx4 v138, s[18:19]
	s_add_i32 m0, s29, 0x16000
	s_add_u32 s30, s6, s12
	s_addc_u32 s31, s7, s13
	s_add_u32 s30, s30, s85
	s_addc_u32 s31, s31, 0
	s_add_i32 s54, s29, 0x2000
	global_load_lds_dwordx4 v134, s[18:19]
	s_mov_b32 m0, s29
	s_add_u32 s12, s30, 0x40000
	global_load_lds_dwordx4 v140, s[30:31]
	s_mov_b32 m0, s54
	s_addc_u32 s13, s31, 0
	s_add_i32 s55, s29, 0x4000
	global_load_lds_dwordx4 v136, s[30:31]
	s_mov_b32 m0, s55
	s_add_i32 s62, s29, 0x6000
	global_load_lds_dwordx4 v140, s[12:13]
	s_mov_b32 m0, s62
	v_mov_b32_e32 v135, v2
	global_load_lds_dwordx4 v136, s[12:13]
	v_mov_b32_e32 v141, v2
	v_mov_b32_e32 v137, v2
	s_cmp_eq_u32 s16, 1
	v_lshl_add_u64 v[10:11], s[36:37], 0, v[138:139]
	v_lshl_add_u64 v[8:9], s[36:37], 0, v[134:135]
	v_lshl_add_u64 v[4:5], s[30:31], 0, v[140:141]
	s_cselect_b64 s[12:13], -1, 0
	s_cmp_lg_u32 s16, 1
	v_lshl_add_u64 v[6:7], s[30:31], 0, v[136:137]
	s_cbranch_scc1 .LBB0_1374
	s_barrier
